# GATE-PF: in a unit's last attention tile iteration every wave touches the two cache lines of its silu(gb) row that the epilogue reads first, hiding their HBM latency (on SUBLN-LDS)
# baseline (speedup 1.0000x reference)
.Lat3_loop:
	s_add_i32 s22, s6, 1
	s_cmp_lg_u32 s6, 2
	s_cselect_b32 s22, s22, 0
	s_add_i32 s23, s22, 1
	s_cmp_lg_u32 s22, 2
	s_cselect_b32 s23, s23, 0
	s_lshl_b32 s24, s6, 14
	s_lshl_b32 s25, s22, 14
	s_lshl_b32 s23, s23, 14
	v_add_u32_e32 v248, s24, v153
	v_add_u32_e32 v159, s25, v141
	ds_read_b64_tr_b16 v[168:169], v248 offset:49152
	ds_read_b64_tr_b16 v[170:171], v248 offset:49664
	ds_read_b64_tr_b16 v[172:173], v248 offset:53248
	ds_read_b64_tr_b16 v[174:175], v248 offset:53760
	ds_read_b64_tr_b16 v[176:177], v248 offset:57344
	ds_read_b64_tr_b16 v[178:179], v248 offset:57856
	ds_read_b64_tr_b16 v[180:181], v248 offset:61440
	ds_read_b64_tr_b16 v[182:183], v248 offset:61952
	s_waitcnt vmcnt(0)
	s_barrier
	ds_read_b128 v[210:213], v159
	ds_read_b128 v[218:221], v159 offset:2048
	ds_read_b128 v[226:229], v159 offset:4096
	ds_read_b128 v[234:237], v159 offset:6144
	s_cmp_eq_u32 s4, 1
	s_cbranch_scc1 .Lat3_last
	s_mov_b32 s28, m0
	s_add_i32 s24, s23, s29
	s_mov_b32 m0, s24
	s_add_i32 s25, s23, s42
	global_load_lds_dwordx4 v[144:145], off
	s_addk_i32 s25, 0xff80
	s_mov_b32 m0, s25
	s_add_i32 s24, s24, 0xc000
	global_load_lds_dwordx4 v[144:145], off offset:128
	s_mov_b32 m0, s24
	s_add_i32 s25, s25, 0xc000
	global_load_lds_dwordx4 v[146:147], off
	s_mov_b32 m0, s25
	v_lshl_add_u64 v[144:145], v[144:145], 0, s[18:19]
	global_load_lds_dwordx4 v[146:147], off offset:128
	s_mov_b32 m0, s28
	v_lshl_add_u64 v[146:147], v[146:147], 0, s[18:19]
	s_branch .Lat3_nodma
.Lat3_last:
	v_lshlrev_b64 v[250:251], 12, v[142:143]
	v_lshl_add_u64 v[250:251], s[10:11], 0, v[250:251]
	s_lshl_b32 s24, s26, 1
	s_mov_b32 s25, 0
	v_lshl_add_u64 v[250:251], v[250:251], 0, s[24:25]
	v_mov_b32_e32 v252, v140
	v_mov_b32_e32 v253, 0
	v_lshl_add_u64 v[250:251], v[250:251], 0, v[252:253]
	s_mov_b32 s24, s37
	v_lshl_add_u64 v[250:251], v[250:251], 0, s[24:25]
	global_load_dword v252, v[250:251], off offset:2048
	global_load_dword v253, v[250:251], off offset:2176
